# MLP2 K-loop: nt cache policy on the A-operand (hidden activations, read once) LDS-DMA loads
# baseline (speedup 1.0000x reference)
; #define PG8_STAGE(bufoff, gbase, voff) do { _Pragma("unroll") for (int _i = 0; _i < 2; ++_i) \
;         __builtin_amdgcn_global_load_lds((const unsigned*)((const char*)(gbase) + (voff)[_i]), (LAS unsigned*)(lds + (bufoff) + ldsw + _i * 8192), 16, 0, 0); } while (0)
; #define PG8_LDA(dst, b, h) do { _Pragma("unroll") for (int m = 0; m < 4; ++m) _Pragma("unroll") for (int k = 0; k < 2; ++k) dst[m][k] = *(const LAS bf16x8*)(lds + PG8_SA(b, h) + aoff + m * 2048 + k * 1024); } while (0)
; #define PG8_LDB(dst, b, h) do { _Pragma("unroll") for (int n = 0; n < 2; ++n) _Pragma("unroll") for (int k = 0; k < 2; ++k) dst[n][k] = *(const LAS bf16x8*)(lds + PG8_SB(b, h) + boff + n * 2048 + k * 1024); } while (0)
; #define PG8_MMA(ai, bj, At, Bt) do { __builtin_amdgcn_s_setprio(1); _Pragma("unroll") for (int m = 0; m < 4; ++m) _Pragma("unroll") for (int n = 0; n < 2; ++n) _Pragma("unroll") for (int k = 0; k < 2; ++k) \
;         acc[ai][bj][m][n] = __builtin_amdgcn_mfma_f32_16x16x32_bf16(Bt[n][k], At[m][k], acc[ai][bj][m][n], 0, 0, 0); __builtin_amdgcn_s_setprio(0); } while (0)
; #define PG8_WAIT_V(n) asm volatile("s_waitcnt vmcnt(" #n ")" ::: "memory")
; #define PG8_WAIT_L(n) asm volatile("s_waitcnt lgkmcnt(" #n ")" ::: "memory")
; #define PG8_BAR __builtin_amdgcn_s_barrier()
; #define PG8_SCHED __builtin_amdgcn_sched_barrier(0)
; template <class Epi, class Sched, bool ALIGN_EPI = false, bool SP2 = false>
; __device__ __forceinline__ void gemm_phase(LAS unsigned char* lds, const Gemm g, const Sched& S, const Epi& E) {
;     ...
;             PG8_LDB(B0, 0, 0); PG8_LDB(B1, 0, 1); PG8_SCHED; PG8_LDA(At, 0, 0); PG8_STAGE(PG8_SA(1, 1), a1 + hstep, voffA);
;             PG8_WAIT_V(8); PG8_WAIT_L(0); PG8_BAR; PG8_MMA(0, 0, At, B0); PG8_MMA(0, 1, At, B1); PG8_BAR; PG8_SCHED;
;             PG8_LDA(At, 0, 1); PG8_STAGE(PG8_SB(0, 0), b2, voffB); PG8_STAGE(PG8_SB(0, 1), b2 + hstep, voffB); PG8_STAGE(PG8_SA(0, 0), a2, voffA);
;             PG8_WAIT_V(8); PG8_WAIT_L(0); PG8_BAR; PG8_MMA(1, 0, At, B0); PG8_MMA(1, 1, At, B1); PG8_BAR; PG8_SCHED;
.LBB0_612:
	s_add_u32 s14, s42, 0xfff00080
	s_addc_u32 s15, s43, -1
	s_add_i32 s16, 0, 0x10000
	s_cmp_eq_u32 s71, 60
	s_cselect_b32 s49, s37, s15
	s_cselect_b32 s48, s54, s14
	s_cselect_b32 s47, s29, s65
	s_cselect_b32 s46, s55, s64
	s_add_i32 s17, 0, 0x14000
	v_add_u32_e32 v140, s16, v175
	v_add_u32_e32 v172, s17, v175
	ds_read_b128 v[128:131], v140
	ds_read_b128 v[132:135], v140 offset:1024
	ds_read_b128 v[136:139], v140 offset:2048
	ds_read_b128 v[140:143], v140 offset:3072
	ds_read_b128 v[164:167], v172
	ds_read_b128 v[168:171], v172 offset:1024
	ds_read_b128 v[180:183], v172 offset:2048
	ds_read_b128 v[184:187], v172 offset:3072
	v_lshl_add_u64 v[172:173], s[42:43], 0, v[150:151]
	s_add_i32 m0, s7, 0xc000
	ds_read_b128 v[188:191], v178
	ds_read_b128 v[192:195], v178 offset:1024
	ds_read_b128 v[196:199], v178 offset:2048
	ds_read_b128 v[200:203], v178 offset:3072
	ds_read_b128 v[218:221], v178 offset:4096
	ds_read_b128 v[222:225], v178 offset:5120
	ds_read_b128 v[226:229], v178 offset:6144
	ds_read_b128 v[230:233], v178 offset:7168
	global_load_lds_dwordx4 v[172:173], off nt
	v_lshl_add_u64 v[172:173], s[42:43], 0, v[162:163]
	s_add_i32 m0, s7, 0xe000
	s_nop 0
	global_load_lds_dwordx4 v[172:173], off nt
	s_waitcnt vmcnt(8)
	s_waitcnt lgkmcnt(0)
	s_barrier
	s_setprio 1
	s_waitcnt lgkmcnt(0)
	v_mfma_f32_16x16x32_bf16 v[124:127], v[128:131], v[188:191], v[124:127]
	v_mfma_f32_16x16x32_bf16 v[120:123], v[136:139], v[188:191], v[120:123]
	v_mfma_f32_16x16x32_bf16 v[112:115], v[128:131], v[196:199], v[112:115]
	v_mfma_f32_16x16x32_bf16 v[104:107], v[136:139], v[196:199], v[104:107]
	v_mfma_f32_16x16x32_bf16 v[92:95], v[128:131], v[218:221], v[92:95]
	v_mfma_f32_16x16x32_bf16 v[88:91], v[136:139], v[218:221], v[88:91]
	v_mfma_f32_16x16x32_bf16 v[76:79], v[128:131], v[226:229], v[76:79]
	v_mfma_f32_16x16x32_bf16 v[72:75], v[136:139], v[226:229], v[72:75]
	v_mfma_f32_16x16x32_bf16 v[124:127], v[132:135], v[192:195], v[124:127]
	v_mfma_f32_16x16x32_bf16 v[120:123], v[140:143], v[192:195], v[120:123]
	v_mfma_f32_16x16x32_bf16 v[112:115], v[132:135], v[200:203], v[112:115]
	v_mfma_f32_16x16x32_bf16 v[104:107], v[140:143], v[200:203], v[104:107]
	v_mfma_f32_16x16x32_bf16 v[92:95], v[132:135], v[222:225], v[92:95]
	v_mfma_f32_16x16x32_bf16 v[88:91], v[140:143], v[222:225], v[88:91]
	v_mfma_f32_16x16x32_bf16 v[76:79], v[132:135], v[230:233], v[76:79]
	v_mfma_f32_16x16x32_bf16 v[72:75], v[140:143], v[230:233], v[72:75]
	s_setprio 0
	s_setprio 1
	v_mfma_f32_16x16x32_bf16 v[116:119], v[164:167], v[188:191], v[116:119]
	v_mfma_f32_16x16x32_bf16 v[108:111], v[180:183], v[188:191], v[108:111]
	v_mfma_f32_16x16x32_bf16 v[100:103], v[164:167], v[196:199], v[100:103]
	v_mfma_f32_16x16x32_bf16 v[96:99], v[180:183], v[196:199], v[96:99]
	v_mfma_f32_16x16x32_bf16 v[84:87], v[164:167], v[218:221], v[84:87]
	v_mfma_f32_16x16x32_bf16 v[80:83], v[180:183], v[218:221], v[80:83]
	v_mfma_f32_16x16x32_bf16 v[68:71], v[164:167], v[226:229], v[68:71]
	v_mfma_f32_16x16x32_bf16 v[64:67], v[180:183], v[226:229], v[64:67]
	v_mfma_f32_16x16x32_bf16 v[116:119], v[168:171], v[192:195], v[116:119]
	v_mfma_f32_16x16x32_bf16 v[108:111], v[184:187], v[192:195], v[108:111]
	v_mfma_f32_16x16x32_bf16 v[100:103], v[168:171], v[200:203], v[100:103]
	v_mfma_f32_16x16x32_bf16 v[96:99], v[184:187], v[200:203], v[96:99]
	v_mfma_f32_16x16x32_bf16 v[84:87], v[168:171], v[222:225], v[84:87]
	v_mfma_f32_16x16x32_bf16 v[80:83], v[184:187], v[222:225], v[80:83]
	v_mfma_f32_16x16x32_bf16 v[68:71], v[168:171], v[230:233], v[68:71]
	v_mfma_f32_16x16x32_bf16 v[64:67], v[184:187], v[230:233], v[64:67]
	s_setprio 0
	s_barrier
	s_add_i32 s14, s16, s6
	v_lshl_add_u64 v[172:173], s[46:47], 0, v[152:153]
	s_mov_b32 m0, s14
	ds_read_b128 v[188:191], v178 offset:16384
	ds_read_b128 v[192:195], v178 offset:17408
	ds_read_b128 v[196:199], v178 offset:18432
	ds_read_b128 v[200:203], v178 offset:19456
	ds_read_b128 v[218:221], v178 offset:20480
	ds_read_b128 v[222:225], v178 offset:21504
	ds_read_b128 v[226:229], v178 offset:22528
	ds_read_b128 v[230:233], v178 offset:23552
	global_load_lds_dwordx4 v[172:173], off
	s_add_i32 m0, s14, 0x2000
	s_add_u32 s14, s46, 0x100000
	v_lshl_add_u64 v[204:205], s[46:47], 0, v[144:145]
	s_addc_u32 s15, s47, 0
	s_add_i32 s16, s17, s6
	global_load_lds_dwordx4 v[204:205], off
	v_lshl_add_u64 v[234:235], s[14:15], 0, v[152:153]
	s_mov_b32 m0, s16
	v_lshl_add_u64 v[236:237], s[48:49], 0, v[146:147]
	global_load_lds_dwordx4 v[234:235], off
	v_lshl_add_u64 v[234:235], s[14:15], 0, v[144:145]
	s_add_i32 m0, s16, 0x2000
	s_nop 0
	global_load_lds_dwordx4 v[234:235], off
	v_lshl_add_u64 v[234:235], s[48:49], 0, v[148:149]
	s_mov_b32 m0, s7
	s_nop 0
	global_load_lds_dwordx4 v[234:235], off nt
	s_mov_b32 m0, s8
	s_nop 0
	global_load_lds_dwordx4 v[236:237], off nt
	s_waitcnt vmcnt(8)
	s_waitcnt lgkmcnt(0)
	s_barrier
; #define PG8_STAGE(bufoff, gbase, voff) do { _Pragma("unroll") for (int _i = 0; _i < 2; ++_i) \
;         __builtin_amdgcn_global_load_lds((const unsigned*)((const char*)(gbase) + (voff)[_i]), (LAS unsigned*)(lds + (bufoff) + ldsw + _i * 8192), 16, 0, 0); } while (0)
; #define PG8_LDA(dst, b, h) do { _Pragma("unroll") for (int m = 0; m < 4; ++m) _Pragma("unroll") for (int k = 0; k < 2; ++k) dst[m][k] = *(const LAS bf16x8*)(lds + PG8_SA(b, h) + aoff + m * 2048 + k * 1024); } while (0)
; #define PG8_LDB(dst, b, h) do { _Pragma("unroll") for (int n = 0; n < 2; ++n) _Pragma("unroll") for (int k = 0; k < 2; ++k) dst[n][k] = *(const LAS bf16x8*)(lds + PG8_SB(b, h) + boff + n * 2048 + k * 1024); } while (0)
; #define PG8_MMA(ai, bj, At, Bt) do { __builtin_amdgcn_s_setprio(1); _Pragma("unroll") for (int m = 0; m < 4; ++m) _Pragma("unroll") for (int n = 0; n < 2; ++n) _Pragma("unroll") for (int k = 0; k < 2; ++k) \
;         acc[ai][bj][m][n] = __builtin_amdgcn_mfma_f32_16x16x32_bf16(Bt[n][k], At[m][k], acc[ai][bj][m][n], 0, 0, 0); __builtin_amdgcn_s_setprio(0); } while (0)
; #define PG8_WAIT_V(n) asm volatile("s_waitcnt vmcnt(" #n ")" ::: "memory")
; #define PG8_WAIT_L(n) asm volatile("s_waitcnt lgkmcnt(" #n ")" ::: "memory")
; #define PG8_BAR __builtin_amdgcn_s_barrier()
; #define PG8_SCHED __builtin_amdgcn_sched_barrier(0)
; template <class Epi, class Sched, bool ALIGN_EPI = false, bool SP2 = false>
; __device__ __forceinline__ void gemm_phase(LAS unsigned char* lds, const Gemm g, const Sched& S, const Epi& E) {
;     ...
;             PG8_WAIT_V(8); PG8_WAIT_L(0); PG8_BAR; PG8_MMA(1, 0, At, B0); PG8_MMA(1, 1, At, B1); PG8_BAR; PG8_SCHED;
;             PG8_LDB(B0, 1, 0); PG8_LDB(B1, 1, 1); PG8_SCHED; PG8_LDA(At, 1, 0); PG8_STAGE(PG8_SA(0, 1), a2 + hstep, voffA);
;             PG8_WAIT_V(8); PG8_WAIT_L(0); PG8_BAR; PG8_MMA(0, 0, At, B0); PG8_MMA(0, 1, At, B1); PG8_BAR; PG8_SCHED;
;             PG8_LDA(At, 1, 1); PG8_STAGE(PG8_SB(1, 0), b3, voffB); PG8_STAGE(PG8_SB(1, 1), b3 + hstep, voffB); PG8_STAGE(PG8_SA(1, 0), a3, voffA);
	s_setprio 1
	s_waitcnt lgkmcnt(0)
	v_mfma_f32_16x16x32_bf16 v[60:63], v[128:131], v[188:191], v[60:63]
	v_mfma_f32_16x16x32_bf16 v[56:59], v[136:139], v[188:191], v[56:59]
	v_mfma_f32_16x16x32_bf16 v[44:47], v[128:131], v[196:199], v[44:47]
	v_mfma_f32_16x16x32_bf16 v[40:43], v[136:139], v[196:199], v[40:43]
	v_mfma_f32_16x16x32_bf16 v[28:31], v[128:131], v[218:221], v[28:31]
	v_mfma_f32_16x16x32_bf16 v[24:27], v[136:139], v[218:221], v[24:27]
	v_mfma_f32_16x16x32_bf16 v[12:15], v[128:131], v[226:229], v[12:15]
	v_mfma_f32_16x16x32_bf16 v[8:11], v[136:139], v[226:229], v[8:11]
	v_mfma_f32_16x16x32_bf16 v[60:63], v[132:135], v[192:195], v[60:63]
	v_mfma_f32_16x16x32_bf16 v[56:59], v[140:143], v[192:195], v[56:59]
	v_mfma_f32_16x16x32_bf16 v[44:47], v[132:135], v[200:203], v[44:47]
	v_mfma_f32_16x16x32_bf16 v[40:43], v[140:143], v[200:203], v[40:43]
	v_mfma_f32_16x16x32_bf16 v[28:31], v[132:135], v[222:225], v[28:31]
	v_mfma_f32_16x16x32_bf16 v[24:27], v[140:143], v[222:225], v[24:27]
	v_mfma_f32_16x16x32_bf16 v[12:15], v[132:135], v[230:233], v[12:15]
	v_mfma_f32_16x16x32_bf16 v[8:11], v[140:143], v[230:233], v[8:11]
	s_setprio 0
	s_setprio 1
	v_mfma_f32_16x16x32_bf16 v[52:55], v[164:167], v[188:191], v[52:55]
	v_mfma_f32_16x16x32_bf16 v[48:51], v[180:183], v[188:191], v[48:51]
	v_mfma_f32_16x16x32_bf16 v[36:39], v[164:167], v[196:199], v[36:39]
	v_mfma_f32_16x16x32_bf16 v[32:35], v[180:183], v[196:199], v[32:35]
	v_mfma_f32_16x16x32_bf16 v[20:23], v[164:167], v[218:221], v[20:23]
	v_mfma_f32_16x16x32_bf16 v[16:19], v[180:183], v[218:221], v[16:19]
	v_mfma_f32_16x16x32_bf16 v[4:7], v[164:167], v[226:229], v[4:7]
	v_mfma_f32_16x16x32_bf16 v[0:3], v[180:183], v[226:229], v[0:3]
	v_mfma_f32_16x16x32_bf16 v[52:55], v[168:171], v[192:195], v[52:55]
	v_mfma_f32_16x16x32_bf16 v[48:51], v[184:187], v[192:195], v[48:51]
	v_mfma_f32_16x16x32_bf16 v[36:39], v[168:171], v[200:203], v[36:39]
	v_mfma_f32_16x16x32_bf16 v[32:35], v[184:187], v[200:203], v[32:35]
	v_mfma_f32_16x16x32_bf16 v[20:23], v[168:171], v[222:225], v[20:23]
	v_mfma_f32_16x16x32_bf16 v[16:19], v[184:187], v[222:225], v[16:19]
	v_mfma_f32_16x16x32_bf16 v[4:7], v[168:171], v[230:233], v[4:7]
	v_mfma_f32_16x16x32_bf16 v[0:3], v[184:187], v[230:233], v[0:3]
	s_setprio 0
	s_barrier
	s_add_i32 s16, 0, 0x18000
	s_add_i32 s17, 0, 0x1c000
	v_add_u32_e32 v140, s16, v175
	v_add_u32_e32 v179, s17, v175
	ds_read_b128 v[128:131], v140
	ds_read_b128 v[132:135], v140 offset:1024
	ds_read_b128 v[136:139], v140 offset:2048
	ds_read_b128 v[140:143], v140 offset:3072
	ds_read_b128 v[164:167], v179
	ds_read_b128 v[168:171], v179 offset:1024
	ds_read_b128 v[180:183], v179 offset:2048
	ds_read_b128 v[184:187], v179 offset:3072
	s_add_u32 s14, s48, 0x100000
	s_addc_u32 s15, s49, 0
	s_mov_b32 m0, s9
	v_lshl_add_u64 v[238:239], s[14:15], 0, v[148:149]
	ds_read_b128 v[188:191], v178 offset:32768
	ds_read_b128 v[192:195], v178 offset:33792
	ds_read_b128 v[196:199], v178 offset:34816
	ds_read_b128 v[200:203], v178 offset:35840
	ds_read_b128 v[218:221], v178 offset:36864
	ds_read_b128 v[222:225], v178 offset:37888
	ds_read_b128 v[226:229], v178 offset:38912
	ds_read_b128 v[230:233], v178 offset:39936
	global_load_lds_dwordx4 v[238:239], off nt
	v_lshl_add_u64 v[238:239], s[14:15], 0, v[146:147]
	s_mov_b32 m0, s10
	s_nop 0
	global_load_lds_dwordx4 v[238:239], off nt
	s_waitcnt vmcnt(8)
	s_waitcnt lgkmcnt(0)
	s_barrier
	s_setprio 1
	s_waitcnt lgkmcnt(0)
	v_mfma_f32_16x16x32_bf16 v[124:127], v[128:131], v[188:191], v[124:127]
	v_mfma_f32_16x16x32_bf16 v[120:123], v[136:139], v[188:191], v[120:123]
	v_mfma_f32_16x16x32_bf16 v[112:115], v[128:131], v[196:199], v[112:115]
	v_mfma_f32_16x16x32_bf16 v[104:107], v[136:139], v[196:199], v[104:107]
	v_mfma_f32_16x16x32_bf16 v[92:95], v[128:131], v[218:221], v[92:95]
	v_mfma_f32_16x16x32_bf16 v[88:91], v[136:139], v[218:221], v[88:91]
	v_mfma_f32_16x16x32_bf16 v[76:79], v[128:131], v[226:229], v[76:79]
	v_mfma_f32_16x16x32_bf16 v[72:75], v[136:139], v[226:229], v[72:75]
	v_mfma_f32_16x16x32_bf16 v[124:127], v[132:135], v[192:195], v[124:127]
	v_mfma_f32_16x16x32_bf16 v[120:123], v[140:143], v[192:195], v[120:123]
	v_mfma_f32_16x16x32_bf16 v[112:115], v[132:135], v[200:203], v[112:115]
	v_mfma_f32_16x16x32_bf16 v[104:107], v[140:143], v[200:203], v[104:107]
	v_mfma_f32_16x16x32_bf16 v[92:95], v[132:135], v[222:225], v[92:95]
	v_mfma_f32_16x16x32_bf16 v[88:91], v[140:143], v[222:225], v[88:91]
	v_mfma_f32_16x16x32_bf16 v[76:79], v[132:135], v[230:233], v[76:79]
	v_mfma_f32_16x16x32_bf16 v[72:75], v[140:143], v[230:233], v[72:75]
	s_setprio 0
	s_setprio 1
	v_mfma_f32_16x16x32_bf16 v[116:119], v[164:167], v[188:191], v[116:119]
	v_mfma_f32_16x16x32_bf16 v[108:111], v[180:183], v[188:191], v[108:111]
	v_mfma_f32_16x16x32_bf16 v[100:103], v[164:167], v[196:199], v[100:103]
	v_mfma_f32_16x16x32_bf16 v[96:99], v[180:183], v[196:199], v[96:99]
	v_mfma_f32_16x16x32_bf16 v[84:87], v[164:167], v[218:221], v[84:87]
	v_mfma_f32_16x16x32_bf16 v[80:83], v[180:183], v[218:221], v[80:83]
	v_mfma_f32_16x16x32_bf16 v[68:71], v[164:167], v[226:229], v[68:71]
	v_mfma_f32_16x16x32_bf16 v[64:67], v[180:183], v[226:229], v[64:67]
	v_mfma_f32_16x16x32_bf16 v[116:119], v[168:171], v[192:195], v[116:119]
	v_mfma_f32_16x16x32_bf16 v[108:111], v[184:187], v[192:195], v[108:111]
	v_mfma_f32_16x16x32_bf16 v[100:103], v[168:171], v[200:203], v[100:103]
	v_mfma_f32_16x16x32_bf16 v[96:99], v[184:187], v[200:203], v[96:99]
	v_mfma_f32_16x16x32_bf16 v[84:87], v[168:171], v[222:225], v[84:87]
	v_mfma_f32_16x16x32_bf16 v[80:83], v[184:187], v[222:225], v[80:83]
	v_mfma_f32_16x16x32_bf16 v[68:71], v[168:171], v[230:233], v[68:71]
	v_mfma_f32_16x16x32_bf16 v[64:67], v[184:187], v[230:233], v[64:67]
	s_setprio 0
	s_barrier
; #define PG8_STAGE(bufoff, gbase, voff) do { _Pragma("unroll") for (int _i = 0; _i < 2; ++_i) \
;         __builtin_amdgcn_global_load_lds((const unsigned*)((const char*)(gbase) + (voff)[_i]), (LAS unsigned*)(lds + (bufoff) + ldsw + _i * 8192), 16, 0, 0); } while (0)
; #define PG8_LDA(dst, b, h) do { _Pragma("unroll") for (int m = 0; m < 4; ++m) _Pragma("unroll") for (int k = 0; k < 2; ++k) dst[m][k] = *(const LAS bf16x8*)(lds + PG8_SA(b, h) + aoff + m * 2048 + k * 1024); } while (0)
; #define PG8_MMA(ai, bj, At, Bt) do { __builtin_amdgcn_s_setprio(1); _Pragma("unroll") for (int m = 0; m < 4; ++m) _Pragma("unroll") for (int n = 0; n < 2; ++n) _Pragma("unroll") for (int k = 0; k < 2; ++k) \
;         acc[ai][bj][m][n] = __builtin_amdgcn_mfma_f32_16x16x32_bf16(Bt[n][k], At[m][k], acc[ai][bj][m][n], 0, 0, 0); __builtin_amdgcn_s_setprio(0); } while (0)
; #define PG8_WAIT_V(n) asm volatile("s_waitcnt vmcnt(" #n ")" ::: "memory")
; #define PG8_WAIT_L(n) asm volatile("s_waitcnt lgkmcnt(" #n ")" ::: "memory")
; #define PG8_BAR __builtin_amdgcn_s_barrier()
; #define PG8_SCHED __builtin_amdgcn_sched_barrier(0)
; template <class Epi, class Sched, bool ALIGN_EPI = false, bool SP2 = false>
; __device__ __forceinline__ void gemm_phase(LAS unsigned char* lds, const Gemm g, const Sched& S, const Epi& E) {
;     ...
;         for (int t = 0; t < nt; t += 2) {
;     ...
;             PG8_LDA(At, 1, 1); PG8_STAGE(PG8_SB(1, 0), b3, voffB); PG8_STAGE(PG8_SB(1, 1), b3 + hstep, voffB); PG8_STAGE(PG8_SA(1, 0), a3, voffA);
;             PG8_WAIT_V(8); PG8_WAIT_L(0); PG8_BAR; PG8_MMA(1, 0, At, B0); PG8_MMA(1, 1, At, B1); PG8_BAR; PG8_SCHED;
	s_add_i32 s14, s16, s6
	v_lshl_add_u64 v[172:173], v[172:173], 0, s[30:31]
	s_mov_b32 m0, s14
	ds_read_b128 v[188:191], v178 offset:49152
	ds_read_b128 v[192:195], v178 offset:50176
	ds_read_b128 v[196:199], v178 offset:51200
	ds_read_b128 v[200:203], v178 offset:52224
	ds_read_b128 v[218:221], v178 offset:53248
	ds_read_b128 v[222:225], v178 offset:54272
	ds_read_b128 v[226:229], v178 offset:55296
	ds_read_b128 v[230:233], v178 offset:56320
	global_load_lds_dwordx4 v[172:173], off
	s_add_i32 m0, s14, 0x2000
	s_add_u32 s14, s46, 0x100080
	v_lshl_add_u64 v[172:173], v[204:205], 0, s[30:31]
	s_addc_u32 s15, s47, 0
	s_add_i32 s16, s17, s6
	global_load_lds_dwordx4 v[172:173], off
	v_lshl_add_u64 v[172:173], s[14:15], 0, v[152:153]
	s_mov_b32 m0, s16
	s_nop 0
	global_load_lds_dwordx4 v[172:173], off
	v_lshl_add_u64 v[172:173], s[14:15], 0, v[144:145]
	s_add_i32 m0, s16, 0x2000
	s_nop 0
	global_load_lds_dwordx4 v[172:173], off
	v_lshl_add_u64 v[172:173], v[234:235], 0, s[30:31]
	s_mov_b32 m0, s12
	s_nop 0
	global_load_lds_dwordx4 v[172:173], off nt
	v_lshl_add_u64 v[172:173], v[236:237], 0, s[30:31]
	s_mov_b32 m0, s13
	s_nop 0
	global_load_lds_dwordx4 v[172:173], off nt
	s_waitcnt vmcnt(8)
	s_waitcnt lgkmcnt(0)
	s_barrier
	s_setprio 1
	s_waitcnt lgkmcnt(0)
	v_mfma_f32_16x16x32_bf16 v[60:63], v[128:131], v[188:191], v[60:63]
	v_mfma_f32_16x16x32_bf16 v[56:59], v[136:139], v[188:191], v[56:59]
	v_mfma_f32_16x16x32_bf16 v[44:47], v[128:131], v[196:199], v[44:47]
	v_mfma_f32_16x16x32_bf16 v[40:43], v[136:139], v[196:199], v[40:43]
	v_mfma_f32_16x16x32_bf16 v[28:31], v[128:131], v[218:221], v[28:31]
	v_mfma_f32_16x16x32_bf16 v[24:27], v[136:139], v[218:221], v[24:27]
	v_mfma_f32_16x16x32_bf16 v[12:15], v[128:131], v[226:229], v[12:15]
	v_mfma_f32_16x16x32_bf16 v[8:11], v[136:139], v[226:229], v[8:11]
	v_mfma_f32_16x16x32_bf16 v[60:63], v[132:135], v[192:195], v[60:63]
	v_mfma_f32_16x16x32_bf16 v[56:59], v[140:143], v[192:195], v[56:59]
	v_mfma_f32_16x16x32_bf16 v[44:47], v[132:135], v[200:203], v[44:47]
	v_mfma_f32_16x16x32_bf16 v[40:43], v[140:143], v[200:203], v[40:43]
	v_mfma_f32_16x16x32_bf16 v[28:31], v[132:135], v[222:225], v[28:31]
	v_mfma_f32_16x16x32_bf16 v[24:27], v[140:143], v[222:225], v[24:27]
	v_mfma_f32_16x16x32_bf16 v[12:15], v[132:135], v[230:233], v[12:15]
	v_mfma_f32_16x16x32_bf16 v[8:11], v[140:143], v[230:233], v[8:11]
	s_setprio 0
	s_setprio 1
	v_mfma_f32_16x16x32_bf16 v[52:55], v[164:167], v[188:191], v[52:55]
	v_mfma_f32_16x16x32_bf16 v[48:51], v[180:183], v[188:191], v[48:51]
	v_mfma_f32_16x16x32_bf16 v[36:39], v[164:167], v[196:199], v[36:39]
	v_mfma_f32_16x16x32_bf16 v[32:35], v[180:183], v[196:199], v[32:35]
	v_mfma_f32_16x16x32_bf16 v[20:23], v[164:167], v[218:221], v[20:23]
	v_mfma_f32_16x16x32_bf16 v[16:19], v[180:183], v[218:221], v[16:19]
	v_mfma_f32_16x16x32_bf16 v[4:7], v[164:167], v[226:229], v[4:7]
	v_mfma_f32_16x16x32_bf16 v[0:3], v[180:183], v[226:229], v[0:3]
	v_mfma_f32_16x16x32_bf16 v[52:55], v[168:171], v[192:195], v[52:55]
	v_mfma_f32_16x16x32_bf16 v[48:51], v[184:187], v[192:195], v[48:51]
	v_mfma_f32_16x16x32_bf16 v[36:39], v[168:171], v[200:203], v[36:39]
	v_mfma_f32_16x16x32_bf16 v[32:35], v[184:187], v[200:203], v[32:35]
	v_mfma_f32_16x16x32_bf16 v[20:23], v[168:171], v[222:225], v[20:23]
	v_mfma_f32_16x16x32_bf16 v[16:19], v[184:187], v[222:225], v[16:19]
	v_mfma_f32_16x16x32_bf16 v[4:7], v[168:171], v[230:233], v[4:7]
	v_mfma_f32_16x16x32_bf16 v[0:3], v[184:187], v[230:233], v[0:3]
	s_setprio 0
	s_barrier
	s_add_i32 s71, s71, 2
	s_add_u32 s42, s42, 0x100
	s_addc_u32 s43, s43, 0
	s_add_u32 s64, s64, 0x100
	s_addc_u32 s65, s65, 0
	s_cmp_gt_u32 s71, 61
	s_cbranch_scc0 .LBB0_612
	s_and_b64 vcc, exec, s[26:27]
	s_cbranch_vccz .LBB0_615
	s_barrier
